# v71 + gate-tile epilogue rewritten: sigmoid scale / +1 / *256-0.5 as packed f32 ops (two elements per instruction), batched transcendental ops
# speedup vs baseline: 1.0045x; 1.0011x over previous
.LBB0_1363:
	s_and_b64 vcc, exec, s[4:5]
	s_cbranch_vccz .LBB0_1538
	v_readlane_b32 s5, v255, 7
	v_mov_b32_e32 v132, 0xbfb8aa3b
	v_mov_b32_e32 v133, 0xbfb8aa3b
	v_mov_b32_e32 v134, 1.0
	v_mov_b32_e32 v135, 1.0
	v_mov_b32_e32 v136, s29
	v_mov_b32_e32 v137, s29
	v_mov_b32_e32 v138, -0.5
	v_mov_b32_e32 v139, -0.5
	s_add_i32 s67, s67, 0x7ffff500
	s_and_b32 s4, s67, 0x7fffff00
	s_or_b32 s4, s4, s5
	s_movk_i32 s20, 0xc00
	v_lshl_add_u32 v2, v226, 4, s4
	v_pk_mul_f32 v[128:129], v[128:129], v[132:133]
	v_pk_mul_f32 v[130:131], v[130:131], v[132:133]
	v_pk_mul_f32 v[124:125], v[124:125], v[132:133]
	v_pk_mul_f32 v[126:127], v[126:127], v[132:133]
	v_pk_mul_f32 v[120:121], v[120:121], v[132:133]
	v_pk_mul_f32 v[122:123], v[122:123], v[132:133]
	v_pk_mul_f32 v[116:117], v[116:117], v[132:133]
	v_pk_mul_f32 v[118:119], v[118:119], v[132:133]
	v_exp_f32_e32 v128, v128
	v_exp_f32_e32 v129, v129
	v_exp_f32_e32 v130, v130
	v_exp_f32_e32 v131, v131
	v_exp_f32_e32 v124, v124
	v_exp_f32_e32 v125, v125
	v_exp_f32_e32 v126, v126
	v_exp_f32_e32 v127, v127
	v_exp_f32_e32 v120, v120
	v_exp_f32_e32 v121, v121
	v_exp_f32_e32 v122, v122
	v_exp_f32_e32 v123, v123
	v_exp_f32_e32 v116, v116
	v_exp_f32_e32 v117, v117
	v_exp_f32_e32 v118, v118
	v_exp_f32_e32 v119, v119
	v_pk_add_f32 v[128:129], v[128:129], v[134:135]
	v_pk_add_f32 v[130:131], v[130:131], v[134:135]
	v_pk_add_f32 v[124:125], v[124:125], v[134:135]
	v_pk_add_f32 v[126:127], v[126:127], v[134:135]
	v_pk_add_f32 v[120:121], v[120:121], v[134:135]
	v_pk_add_f32 v[122:123], v[122:123], v[134:135]
	v_pk_add_f32 v[116:117], v[116:117], v[134:135]
	v_pk_add_f32 v[118:119], v[118:119], v[134:135]
	v_rcp_f32_e32 v128, v128
	v_rcp_f32_e32 v129, v129
	v_rcp_f32_e32 v130, v130
	v_rcp_f32_e32 v131, v131
	v_rcp_f32_e32 v124, v124
	v_rcp_f32_e32 v125, v125
	v_rcp_f32_e32 v126, v126
	v_rcp_f32_e32 v127, v127
	v_rcp_f32_e32 v120, v120
	v_rcp_f32_e32 v121, v121
	v_rcp_f32_e32 v122, v122
	v_rcp_f32_e32 v123, v123
	v_rcp_f32_e32 v116, v116
	v_rcp_f32_e32 v117, v117
	v_rcp_f32_e32 v118, v118
	v_rcp_f32_e32 v119, v119
	v_pk_fma_f32 v[128:129], v[128:129], v[136:137], v[138:139]
	v_pk_fma_f32 v[130:131], v[130:131], v[136:137], v[138:139]
	v_pk_fma_f32 v[124:125], v[124:125], v[136:137], v[138:139]
	v_pk_fma_f32 v[126:127], v[126:127], v[136:137], v[138:139]
	v_pk_fma_f32 v[120:121], v[120:121], v[136:137], v[138:139]
	v_pk_fma_f32 v[122:123], v[122:123], v[136:137], v[138:139]
	v_pk_fma_f32 v[116:117], v[116:117], v[136:137], v[138:139]
	v_pk_fma_f32 v[118:119], v[118:119], v[136:137], v[138:139]
	v_cvt_pk_u8_f32 v140, v128, 0, 0
	v_cvt_pk_u8_f32 v141, v124, 0, 0
	v_cvt_pk_u8_f32 v142, v120, 0, 0
	v_cvt_pk_u8_f32 v143, v116, 0, 0
	v_cvt_pk_u8_f32 v140, v129, 1, v140
	v_cvt_pk_u8_f32 v141, v125, 1, v141
	v_cvt_pk_u8_f32 v142, v121, 1, v142
	v_cvt_pk_u8_f32 v143, v117, 1, v143
	v_cvt_pk_u8_f32 v140, v130, 2, v140
	v_cvt_pk_u8_f32 v141, v126, 2, v141
	v_cvt_pk_u8_f32 v142, v122, 2, v142
	v_cvt_pk_u8_f32 v143, v118, 2, v143
	v_cvt_pk_u8_f32 v140, v131, 3, v140
	v_cvt_pk_u8_f32 v141, v127, 3, v141
	v_cvt_pk_u8_f32 v142, v123, 3, v142
	v_cvt_pk_u8_f32 v143, v119, 3, v143
	v_mad_u64_u32 v[144:145], s[4:5], v225, s20, v[2:3]
	global_store_dwordx4 v144, v[140:143], s[72:73] nt
	v_pk_mul_f32 v[112:113], v[112:113], v[132:133]
	v_pk_mul_f32 v[114:115], v[114:115], v[132:133]
	v_pk_mul_f32 v[108:109], v[108:109], v[132:133]
	v_pk_mul_f32 v[110:111], v[110:111], v[132:133]
	v_pk_mul_f32 v[104:105], v[104:105], v[132:133]
	v_pk_mul_f32 v[106:107], v[106:107], v[132:133]
	v_pk_mul_f32 v[100:101], v[100:101], v[132:133]
	v_pk_mul_f32 v[102:103], v[102:103], v[132:133]
	v_exp_f32_e32 v112, v112
	v_exp_f32_e32 v113, v113
	v_exp_f32_e32 v114, v114
	v_exp_f32_e32 v115, v115
	v_exp_f32_e32 v108, v108
	v_exp_f32_e32 v109, v109
	v_exp_f32_e32 v110, v110
	v_exp_f32_e32 v111, v111
	v_exp_f32_e32 v104, v104
	v_exp_f32_e32 v105, v105
	v_exp_f32_e32 v106, v106
	v_exp_f32_e32 v107, v107
	v_exp_f32_e32 v100, v100
	v_exp_f32_e32 v101, v101
	v_exp_f32_e32 v102, v102
	v_exp_f32_e32 v103, v103
	v_pk_add_f32 v[112:113], v[112:113], v[134:135]
	v_pk_add_f32 v[114:115], v[114:115], v[134:135]
	v_pk_add_f32 v[108:109], v[108:109], v[134:135]
	v_pk_add_f32 v[110:111], v[110:111], v[134:135]
	v_pk_add_f32 v[104:105], v[104:105], v[134:135]
	v_pk_add_f32 v[106:107], v[106:107], v[134:135]
	v_pk_add_f32 v[100:101], v[100:101], v[134:135]
	v_pk_add_f32 v[102:103], v[102:103], v[134:135]
	v_rcp_f32_e32 v112, v112
	v_rcp_f32_e32 v113, v113
	v_rcp_f32_e32 v114, v114
	v_rcp_f32_e32 v115, v115
	v_rcp_f32_e32 v108, v108
	v_rcp_f32_e32 v109, v109
	v_rcp_f32_e32 v110, v110
	v_rcp_f32_e32 v111, v111
	v_rcp_f32_e32 v104, v104
	v_rcp_f32_e32 v105, v105
	v_rcp_f32_e32 v106, v106
	v_rcp_f32_e32 v107, v107
	v_rcp_f32_e32 v100, v100
	v_rcp_f32_e32 v101, v101
	v_rcp_f32_e32 v102, v102
	v_rcp_f32_e32 v103, v103
	v_pk_fma_f32 v[112:113], v[112:113], v[136:137], v[138:139]
	v_pk_fma_f32 v[114:115], v[114:115], v[136:137], v[138:139]
	v_pk_fma_f32 v[108:109], v[108:109], v[136:137], v[138:139]
	v_pk_fma_f32 v[110:111], v[110:111], v[136:137], v[138:139]
	v_pk_fma_f32 v[104:105], v[104:105], v[136:137], v[138:139]
	v_pk_fma_f32 v[106:107], v[106:107], v[136:137], v[138:139]
	v_pk_fma_f32 v[100:101], v[100:101], v[136:137], v[138:139]
	v_pk_fma_f32 v[102:103], v[102:103], v[136:137], v[138:139]
	v_cvt_pk_u8_f32 v148, v112, 0, 0
	v_cvt_pk_u8_f32 v149, v108, 0, 0
	v_cvt_pk_u8_f32 v150, v104, 0, 0
	v_cvt_pk_u8_f32 v151, v100, 0, 0
	v_cvt_pk_u8_f32 v148, v113, 1, v148
	v_cvt_pk_u8_f32 v149, v109, 1, v149
	v_cvt_pk_u8_f32 v150, v105, 1, v150
	v_cvt_pk_u8_f32 v151, v101, 1, v151
	v_cvt_pk_u8_f32 v148, v114, 2, v148
	v_cvt_pk_u8_f32 v149, v110, 2, v149
	v_cvt_pk_u8_f32 v150, v106, 2, v150
	v_cvt_pk_u8_f32 v151, v102, 2, v151
	v_cvt_pk_u8_f32 v148, v115, 3, v148
	v_cvt_pk_u8_f32 v149, v111, 3, v149
	v_cvt_pk_u8_f32 v150, v107, 3, v150
	v_cvt_pk_u8_f32 v151, v103, 3, v151
	v_mad_u64_u32 v[152:153], s[4:5], v224, s20, v[2:3]
	global_store_dwordx4 v152, v[148:151], s[72:73] nt
	v_pk_mul_f32 v[96:97], v[96:97], v[132:133]
	v_pk_mul_f32 v[98:99], v[98:99], v[132:133]
	v_pk_mul_f32 v[92:93], v[92:93], v[132:133]
	v_pk_mul_f32 v[94:95], v[94:95], v[132:133]
	v_pk_mul_f32 v[88:89], v[88:89], v[132:133]
	v_pk_mul_f32 v[90:91], v[90:91], v[132:133]
	v_pk_mul_f32 v[84:85], v[84:85], v[132:133]
	v_pk_mul_f32 v[86:87], v[86:87], v[132:133]
	v_exp_f32_e32 v96, v96
	v_exp_f32_e32 v97, v97
	v_exp_f32_e32 v98, v98
	v_exp_f32_e32 v99, v99
	v_exp_f32_e32 v92, v92
	v_exp_f32_e32 v93, v93
	v_exp_f32_e32 v94, v94
	v_exp_f32_e32 v95, v95
	v_exp_f32_e32 v88, v88
	v_exp_f32_e32 v89, v89
	v_exp_f32_e32 v90, v90
	v_exp_f32_e32 v91, v91
	v_exp_f32_e32 v84, v84
	v_exp_f32_e32 v85, v85
	v_exp_f32_e32 v86, v86
	v_exp_f32_e32 v87, v87
	v_pk_add_f32 v[96:97], v[96:97], v[134:135]
	v_pk_add_f32 v[98:99], v[98:99], v[134:135]
	v_pk_add_f32 v[92:93], v[92:93], v[134:135]
	v_pk_add_f32 v[94:95], v[94:95], v[134:135]
	v_pk_add_f32 v[88:89], v[88:89], v[134:135]
	v_pk_add_f32 v[90:91], v[90:91], v[134:135]
	v_pk_add_f32 v[84:85], v[84:85], v[134:135]
	v_pk_add_f32 v[86:87], v[86:87], v[134:135]
	v_rcp_f32_e32 v96, v96
	v_rcp_f32_e32 v97, v97
	v_rcp_f32_e32 v98, v98
	v_rcp_f32_e32 v99, v99
	v_rcp_f32_e32 v92, v92
	v_rcp_f32_e32 v93, v93
	v_rcp_f32_e32 v94, v94
	v_rcp_f32_e32 v95, v95
	v_rcp_f32_e32 v88, v88
	v_rcp_f32_e32 v89, v89
	v_rcp_f32_e32 v90, v90
	v_rcp_f32_e32 v91, v91
	v_rcp_f32_e32 v84, v84
	v_rcp_f32_e32 v85, v85
	v_rcp_f32_e32 v86, v86
	v_rcp_f32_e32 v87, v87
	v_pk_fma_f32 v[96:97], v[96:97], v[136:137], v[138:139]
	v_pk_fma_f32 v[98:99], v[98:99], v[136:137], v[138:139]
	v_pk_fma_f32 v[92:93], v[92:93], v[136:137], v[138:139]
	v_pk_fma_f32 v[94:95], v[94:95], v[136:137], v[138:139]
	v_pk_fma_f32 v[88:89], v[88:89], v[136:137], v[138:139]
	v_pk_fma_f32 v[90:91], v[90:91], v[136:137], v[138:139]
	v_pk_fma_f32 v[84:85], v[84:85], v[136:137], v[138:139]
	v_pk_fma_f32 v[86:87], v[86:87], v[136:137], v[138:139]
	v_cvt_pk_u8_f32 v140, v96, 0, 0
	v_cvt_pk_u8_f32 v141, v92, 0, 0
	v_cvt_pk_u8_f32 v142, v88, 0, 0
	v_cvt_pk_u8_f32 v143, v84, 0, 0
	v_cvt_pk_u8_f32 v140, v97, 1, v140
	v_cvt_pk_u8_f32 v141, v93, 1, v141
	v_cvt_pk_u8_f32 v142, v89, 1, v142
	v_cvt_pk_u8_f32 v143, v85, 1, v143
	v_cvt_pk_u8_f32 v140, v98, 2, v140
	v_cvt_pk_u8_f32 v141, v94, 2, v141
	v_cvt_pk_u8_f32 v142, v90, 2, v142
	v_cvt_pk_u8_f32 v143, v86, 2, v143
	v_cvt_pk_u8_f32 v140, v99, 3, v140
	v_cvt_pk_u8_f32 v141, v95, 3, v141
	v_cvt_pk_u8_f32 v142, v91, 3, v142
	v_cvt_pk_u8_f32 v143, v87, 3, v143
	v_mad_u64_u32 v[144:145], s[4:5], v223, s20, v[2:3]
	global_store_dwordx4 v144, v[140:143], s[72:73] nt
	v_pk_mul_f32 v[80:81], v[80:81], v[132:133]
	v_pk_mul_f32 v[82:83], v[82:83], v[132:133]
	v_pk_mul_f32 v[76:77], v[76:77], v[132:133]
	v_pk_mul_f32 v[78:79], v[78:79], v[132:133]
	v_pk_mul_f32 v[72:73], v[72:73], v[132:133]
	v_pk_mul_f32 v[74:75], v[74:75], v[132:133]
	v_pk_mul_f32 v[68:69], v[68:69], v[132:133]
	v_pk_mul_f32 v[70:71], v[70:71], v[132:133]
	v_exp_f32_e32 v80, v80
	v_exp_f32_e32 v81, v81
	v_exp_f32_e32 v82, v82
	v_exp_f32_e32 v83, v83
	v_exp_f32_e32 v76, v76
	v_exp_f32_e32 v77, v77
	v_exp_f32_e32 v78, v78
	v_exp_f32_e32 v79, v79
	v_exp_f32_e32 v72, v72
	v_exp_f32_e32 v73, v73
	v_exp_f32_e32 v74, v74
	v_exp_f32_e32 v75, v75
	v_exp_f32_e32 v68, v68
	v_exp_f32_e32 v69, v69
	v_exp_f32_e32 v70, v70
	v_exp_f32_e32 v71, v71
	v_pk_add_f32 v[80:81], v[80:81], v[134:135]
	v_pk_add_f32 v[82:83], v[82:83], v[134:135]
	v_pk_add_f32 v[76:77], v[76:77], v[134:135]
	v_pk_add_f32 v[78:79], v[78:79], v[134:135]
	v_pk_add_f32 v[72:73], v[72:73], v[134:135]
	v_pk_add_f32 v[74:75], v[74:75], v[134:135]
	v_pk_add_f32 v[68:69], v[68:69], v[134:135]
	v_pk_add_f32 v[70:71], v[70:71], v[134:135]
	v_rcp_f32_e32 v80, v80
	v_rcp_f32_e32 v81, v81
	v_rcp_f32_e32 v82, v82
	v_rcp_f32_e32 v83, v83
	v_rcp_f32_e32 v76, v76
	v_rcp_f32_e32 v77, v77
	v_rcp_f32_e32 v78, v78
	v_rcp_f32_e32 v79, v79
	v_rcp_f32_e32 v72, v72
	v_rcp_f32_e32 v73, v73
	v_rcp_f32_e32 v74, v74
	v_rcp_f32_e32 v75, v75
	v_rcp_f32_e32 v68, v68
	v_rcp_f32_e32 v69, v69
	v_rcp_f32_e32 v70, v70
	v_rcp_f32_e32 v71, v71
	v_pk_fma_f32 v[80:81], v[80:81], v[136:137], v[138:139]
	v_pk_fma_f32 v[82:83], v[82:83], v[136:137], v[138:139]
	v_pk_fma_f32 v[76:77], v[76:77], v[136:137], v[138:139]
	v_pk_fma_f32 v[78:79], v[78:79], v[136:137], v[138:139]
	v_pk_fma_f32 v[72:73], v[72:73], v[136:137], v[138:139]
	v_pk_fma_f32 v[74:75], v[74:75], v[136:137], v[138:139]
	v_pk_fma_f32 v[68:69], v[68:69], v[136:137], v[138:139]
	v_pk_fma_f32 v[70:71], v[70:71], v[136:137], v[138:139]
	v_cvt_pk_u8_f32 v148, v80, 0, 0
	v_cvt_pk_u8_f32 v149, v76, 0, 0
	v_cvt_pk_u8_f32 v150, v72, 0, 0
	v_cvt_pk_u8_f32 v151, v68, 0, 0
	v_cvt_pk_u8_f32 v148, v81, 1, v148
	v_cvt_pk_u8_f32 v149, v77, 1, v149
	v_cvt_pk_u8_f32 v150, v73, 1, v150
	v_cvt_pk_u8_f32 v151, v69, 1, v151
	v_cvt_pk_u8_f32 v148, v82, 2, v148
	v_cvt_pk_u8_f32 v149, v78, 2, v149
	v_cvt_pk_u8_f32 v150, v74, 2, v150
	v_cvt_pk_u8_f32 v151, v70, 2, v151
	v_cvt_pk_u8_f32 v148, v83, 3, v148
	v_cvt_pk_u8_f32 v149, v79, 3, v149
	v_cvt_pk_u8_f32 v150, v75, 3, v150
	v_cvt_pk_u8_f32 v151, v71, 3, v151
	v_mad_u64_u32 v[152:153], s[4:5], v222, s20, v[2:3]
	global_store_dwordx4 v152, v[148:151], s[72:73] nt
	v_pk_mul_f32 v[64:65], v[64:65], v[132:133]
	v_pk_mul_f32 v[66:67], v[66:67], v[132:133]
	v_pk_mul_f32 v[60:61], v[60:61], v[132:133]
	v_pk_mul_f32 v[62:63], v[62:63], v[132:133]
	v_pk_mul_f32 v[56:57], v[56:57], v[132:133]
	v_pk_mul_f32 v[58:59], v[58:59], v[132:133]
	v_pk_mul_f32 v[52:53], v[52:53], v[132:133]
	v_pk_mul_f32 v[54:55], v[54:55], v[132:133]
	v_exp_f32_e32 v64, v64
	v_exp_f32_e32 v65, v65
	v_exp_f32_e32 v66, v66
	v_exp_f32_e32 v67, v67
	v_exp_f32_e32 v60, v60
	v_exp_f32_e32 v61, v61
	v_exp_f32_e32 v62, v62
	v_exp_f32_e32 v63, v63
	v_exp_f32_e32 v56, v56
	v_exp_f32_e32 v57, v57
	v_exp_f32_e32 v58, v58
	v_exp_f32_e32 v59, v59
	v_exp_f32_e32 v52, v52
	v_exp_f32_e32 v53, v53
	v_exp_f32_e32 v54, v54
	v_exp_f32_e32 v55, v55
	v_pk_add_f32 v[64:65], v[64:65], v[134:135]
	v_pk_add_f32 v[66:67], v[66:67], v[134:135]
	v_pk_add_f32 v[60:61], v[60:61], v[134:135]
	v_pk_add_f32 v[62:63], v[62:63], v[134:135]
	v_pk_add_f32 v[56:57], v[56:57], v[134:135]
	v_pk_add_f32 v[58:59], v[58:59], v[134:135]
	v_pk_add_f32 v[52:53], v[52:53], v[134:135]
	v_pk_add_f32 v[54:55], v[54:55], v[134:135]
	v_rcp_f32_e32 v64, v64
	v_rcp_f32_e32 v65, v65
	v_rcp_f32_e32 v66, v66
	v_rcp_f32_e32 v67, v67
	v_rcp_f32_e32 v60, v60
	v_rcp_f32_e32 v61, v61
	v_rcp_f32_e32 v62, v62
	v_rcp_f32_e32 v63, v63
	v_rcp_f32_e32 v56, v56
	v_rcp_f32_e32 v57, v57
	v_rcp_f32_e32 v58, v58
	v_rcp_f32_e32 v59, v59
	v_rcp_f32_e32 v52, v52
	v_rcp_f32_e32 v53, v53
	v_rcp_f32_e32 v54, v54
	v_rcp_f32_e32 v55, v55
	v_pk_fma_f32 v[64:65], v[64:65], v[136:137], v[138:139]
	v_pk_fma_f32 v[66:67], v[66:67], v[136:137], v[138:139]
	v_pk_fma_f32 v[60:61], v[60:61], v[136:137], v[138:139]
	v_pk_fma_f32 v[62:63], v[62:63], v[136:137], v[138:139]
	v_pk_fma_f32 v[56:57], v[56:57], v[136:137], v[138:139]
	v_pk_fma_f32 v[58:59], v[58:59], v[136:137], v[138:139]
	v_pk_fma_f32 v[52:53], v[52:53], v[136:137], v[138:139]
	v_pk_fma_f32 v[54:55], v[54:55], v[136:137], v[138:139]
	v_cvt_pk_u8_f32 v140, v64, 0, 0
	v_cvt_pk_u8_f32 v141, v60, 0, 0
	v_cvt_pk_u8_f32 v142, v56, 0, 0
	v_cvt_pk_u8_f32 v143, v52, 0, 0
	v_cvt_pk_u8_f32 v140, v65, 1, v140
	v_cvt_pk_u8_f32 v141, v61, 1, v141
	v_cvt_pk_u8_f32 v142, v57, 1, v142
	v_cvt_pk_u8_f32 v143, v53, 1, v143
	v_cvt_pk_u8_f32 v140, v66, 2, v140
	v_cvt_pk_u8_f32 v141, v62, 2, v141
	v_cvt_pk_u8_f32 v142, v58, 2, v142
	v_cvt_pk_u8_f32 v143, v54, 2, v143
	v_cvt_pk_u8_f32 v140, v67, 3, v140
	v_cvt_pk_u8_f32 v141, v63, 3, v141
	v_cvt_pk_u8_f32 v142, v59, 3, v142
	v_cvt_pk_u8_f32 v143, v55, 3, v143
	v_mad_u64_u32 v[144:145], s[4:5], v221, s20, v[2:3]
	global_store_dwordx4 v144, v[140:143], s[72:73] nt
	v_pk_mul_f32 v[48:49], v[48:49], v[132:133]
	v_pk_mul_f32 v[50:51], v[50:51], v[132:133]
	v_pk_mul_f32 v[44:45], v[44:45], v[132:133]
	v_pk_mul_f32 v[46:47], v[46:47], v[132:133]
	v_pk_mul_f32 v[40:41], v[40:41], v[132:133]
	v_pk_mul_f32 v[42:43], v[42:43], v[132:133]
	v_pk_mul_f32 v[36:37], v[36:37], v[132:133]
	v_pk_mul_f32 v[38:39], v[38:39], v[132:133]
	v_exp_f32_e32 v48, v48
	v_exp_f32_e32 v49, v49
	v_exp_f32_e32 v50, v50
	v_exp_f32_e32 v51, v51
	v_exp_f32_e32 v44, v44
	v_exp_f32_e32 v45, v45
	v_exp_f32_e32 v46, v46
	v_exp_f32_e32 v47, v47
	v_exp_f32_e32 v40, v40
	v_exp_f32_e32 v41, v41
	v_exp_f32_e32 v42, v42
	v_exp_f32_e32 v43, v43
	v_exp_f32_e32 v36, v36
	v_exp_f32_e32 v37, v37
	v_exp_f32_e32 v38, v38
	v_exp_f32_e32 v39, v39
	v_pk_add_f32 v[48:49], v[48:49], v[134:135]
	v_pk_add_f32 v[50:51], v[50:51], v[134:135]
	v_pk_add_f32 v[44:45], v[44:45], v[134:135]
	v_pk_add_f32 v[46:47], v[46:47], v[134:135]
	v_pk_add_f32 v[40:41], v[40:41], v[134:135]
	v_pk_add_f32 v[42:43], v[42:43], v[134:135]
	v_pk_add_f32 v[36:37], v[36:37], v[134:135]
	v_pk_add_f32 v[38:39], v[38:39], v[134:135]
	v_rcp_f32_e32 v48, v48
	v_rcp_f32_e32 v49, v49
	v_rcp_f32_e32 v50, v50
	v_rcp_f32_e32 v51, v51
	v_rcp_f32_e32 v44, v44
	v_rcp_f32_e32 v45, v45
	v_rcp_f32_e32 v46, v46
	v_rcp_f32_e32 v47, v47
	v_rcp_f32_e32 v40, v40
	v_rcp_f32_e32 v41, v41
	v_rcp_f32_e32 v42, v42
	v_rcp_f32_e32 v43, v43
	v_rcp_f32_e32 v36, v36
	v_rcp_f32_e32 v37, v37
	v_rcp_f32_e32 v38, v38
	v_rcp_f32_e32 v39, v39
	v_pk_fma_f32 v[48:49], v[48:49], v[136:137], v[138:139]
	v_pk_fma_f32 v[50:51], v[50:51], v[136:137], v[138:139]
	v_pk_fma_f32 v[44:45], v[44:45], v[136:137], v[138:139]
	v_pk_fma_f32 v[46:47], v[46:47], v[136:137], v[138:139]
	v_pk_fma_f32 v[40:41], v[40:41], v[136:137], v[138:139]
	v_pk_fma_f32 v[42:43], v[42:43], v[136:137], v[138:139]
	v_pk_fma_f32 v[36:37], v[36:37], v[136:137], v[138:139]
	v_pk_fma_f32 v[38:39], v[38:39], v[136:137], v[138:139]
	v_cvt_pk_u8_f32 v148, v48, 0, 0
	v_cvt_pk_u8_f32 v149, v44, 0, 0
	v_cvt_pk_u8_f32 v150, v40, 0, 0
	v_cvt_pk_u8_f32 v151, v36, 0, 0
	v_cvt_pk_u8_f32 v148, v49, 1, v148
	v_cvt_pk_u8_f32 v149, v45, 1, v149
	v_cvt_pk_u8_f32 v150, v41, 1, v150
	v_cvt_pk_u8_f32 v151, v37, 1, v151
	v_cvt_pk_u8_f32 v148, v50, 2, v148
	v_cvt_pk_u8_f32 v149, v46, 2, v149
	v_cvt_pk_u8_f32 v150, v42, 2, v150
	v_cvt_pk_u8_f32 v151, v38, 2, v151
	v_cvt_pk_u8_f32 v148, v51, 3, v148
	v_cvt_pk_u8_f32 v149, v47, 3, v149
	v_cvt_pk_u8_f32 v150, v43, 3, v150
	v_cvt_pk_u8_f32 v151, v39, 3, v151
	v_mad_u64_u32 v[152:153], s[4:5], v220, s20, v[2:3]
	global_store_dwordx4 v152, v[148:151], s[72:73] nt
	v_pk_mul_f32 v[32:33], v[32:33], v[132:133]
	v_pk_mul_f32 v[34:35], v[34:35], v[132:133]
	v_pk_mul_f32 v[28:29], v[28:29], v[132:133]
	v_pk_mul_f32 v[30:31], v[30:31], v[132:133]
	v_pk_mul_f32 v[24:25], v[24:25], v[132:133]
	v_pk_mul_f32 v[26:27], v[26:27], v[132:133]
	v_pk_mul_f32 v[20:21], v[20:21], v[132:133]
	v_pk_mul_f32 v[22:23], v[22:23], v[132:133]
	v_exp_f32_e32 v32, v32
	v_exp_f32_e32 v33, v33
	v_exp_f32_e32 v34, v34
	v_exp_f32_e32 v35, v35
	v_exp_f32_e32 v28, v28
	v_exp_f32_e32 v29, v29
	v_exp_f32_e32 v30, v30
	v_exp_f32_e32 v31, v31
	v_exp_f32_e32 v24, v24
	v_exp_f32_e32 v25, v25
	v_exp_f32_e32 v26, v26
	v_exp_f32_e32 v27, v27
	v_exp_f32_e32 v20, v20
	v_exp_f32_e32 v21, v21
	v_exp_f32_e32 v22, v22
	v_exp_f32_e32 v23, v23
	v_pk_add_f32 v[32:33], v[32:33], v[134:135]
	v_pk_add_f32 v[34:35], v[34:35], v[134:135]
	v_pk_add_f32 v[28:29], v[28:29], v[134:135]
	v_pk_add_f32 v[30:31], v[30:31], v[134:135]
	v_pk_add_f32 v[24:25], v[24:25], v[134:135]
	v_pk_add_f32 v[26:27], v[26:27], v[134:135]
	v_pk_add_f32 v[20:21], v[20:21], v[134:135]
	v_pk_add_f32 v[22:23], v[22:23], v[134:135]
	v_rcp_f32_e32 v32, v32
	v_rcp_f32_e32 v33, v33
	v_rcp_f32_e32 v34, v34
	v_rcp_f32_e32 v35, v35
	v_rcp_f32_e32 v28, v28
	v_rcp_f32_e32 v29, v29
	v_rcp_f32_e32 v30, v30
	v_rcp_f32_e32 v31, v31
	v_rcp_f32_e32 v24, v24
	v_rcp_f32_e32 v25, v25
	v_rcp_f32_e32 v26, v26
	v_rcp_f32_e32 v27, v27
	v_rcp_f32_e32 v20, v20
	v_rcp_f32_e32 v21, v21
	v_rcp_f32_e32 v22, v22
	v_rcp_f32_e32 v23, v23
	v_pk_fma_f32 v[32:33], v[32:33], v[136:137], v[138:139]
	v_pk_fma_f32 v[34:35], v[34:35], v[136:137], v[138:139]
	v_pk_fma_f32 v[28:29], v[28:29], v[136:137], v[138:139]
	v_pk_fma_f32 v[30:31], v[30:31], v[136:137], v[138:139]
	v_pk_fma_f32 v[24:25], v[24:25], v[136:137], v[138:139]
	v_pk_fma_f32 v[26:27], v[26:27], v[136:137], v[138:139]
	v_pk_fma_f32 v[20:21], v[20:21], v[136:137], v[138:139]
	v_pk_fma_f32 v[22:23], v[22:23], v[136:137], v[138:139]
	v_cvt_pk_u8_f32 v140, v32, 0, 0
	v_cvt_pk_u8_f32 v141, v28, 0, 0
	v_cvt_pk_u8_f32 v142, v24, 0, 0
	v_cvt_pk_u8_f32 v143, v20, 0, 0
	v_cvt_pk_u8_f32 v140, v33, 1, v140
	v_cvt_pk_u8_f32 v141, v29, 1, v141
	v_cvt_pk_u8_f32 v142, v25, 1, v142
	v_cvt_pk_u8_f32 v143, v21, 1, v143
	v_cvt_pk_u8_f32 v140, v34, 2, v140
	v_cvt_pk_u8_f32 v141, v30, 2, v141
	v_cvt_pk_u8_f32 v142, v26, 2, v142
	v_cvt_pk_u8_f32 v143, v22, 2, v143
	v_cvt_pk_u8_f32 v140, v35, 3, v140
	v_cvt_pk_u8_f32 v141, v31, 3, v141
	v_cvt_pk_u8_f32 v142, v27, 3, v142
	v_cvt_pk_u8_f32 v143, v23, 3, v143
	v_mad_u64_u32 v[144:145], s[4:5], v195, s20, v[2:3]
	global_store_dwordx4 v144, v[140:143], s[72:73] nt
	v_pk_mul_f32 v[16:17], v[16:17], v[132:133]
	v_pk_mul_f32 v[18:19], v[18:19], v[132:133]
	v_pk_mul_f32 v[12:13], v[12:13], v[132:133]
	v_pk_mul_f32 v[14:15], v[14:15], v[132:133]
	v_pk_mul_f32 v[8:9], v[8:9], v[132:133]
	v_pk_mul_f32 v[10:11], v[10:11], v[132:133]
	v_pk_mul_f32 v[4:5], v[4:5], v[132:133]
	v_pk_mul_f32 v[6:7], v[6:7], v[132:133]
	v_exp_f32_e32 v16, v16
	v_exp_f32_e32 v17, v17
	v_exp_f32_e32 v18, v18
	v_exp_f32_e32 v19, v19
	v_exp_f32_e32 v12, v12
	v_exp_f32_e32 v13, v13
	v_exp_f32_e32 v14, v14
	v_exp_f32_e32 v15, v15
	v_exp_f32_e32 v8, v8
	v_exp_f32_e32 v9, v9
	v_exp_f32_e32 v10, v10
	v_exp_f32_e32 v11, v11
	v_exp_f32_e32 v4, v4
	v_exp_f32_e32 v5, v5
	v_exp_f32_e32 v6, v6
	v_exp_f32_e32 v7, v7
	v_pk_add_f32 v[16:17], v[16:17], v[134:135]
	v_pk_add_f32 v[18:19], v[18:19], v[134:135]
	v_pk_add_f32 v[12:13], v[12:13], v[134:135]
	v_pk_add_f32 v[14:15], v[14:15], v[134:135]
	v_pk_add_f32 v[8:9], v[8:9], v[134:135]
	v_pk_add_f32 v[10:11], v[10:11], v[134:135]
	v_pk_add_f32 v[4:5], v[4:5], v[134:135]
	v_pk_add_f32 v[6:7], v[6:7], v[134:135]
	v_rcp_f32_e32 v16, v16
	v_rcp_f32_e32 v17, v17
	v_rcp_f32_e32 v18, v18
	v_rcp_f32_e32 v19, v19
	v_rcp_f32_e32 v12, v12
	v_rcp_f32_e32 v13, v13
	v_rcp_f32_e32 v14, v14
	v_rcp_f32_e32 v15, v15
	v_rcp_f32_e32 v8, v8
	v_rcp_f32_e32 v9, v9
	v_rcp_f32_e32 v10, v10
	v_rcp_f32_e32 v11, v11
	v_rcp_f32_e32 v4, v4
	v_rcp_f32_e32 v5, v5
	v_rcp_f32_e32 v6, v6
	v_rcp_f32_e32 v7, v7
	v_pk_fma_f32 v[16:17], v[16:17], v[136:137], v[138:139]
	v_pk_fma_f32 v[18:19], v[18:19], v[136:137], v[138:139]
	v_pk_fma_f32 v[12:13], v[12:13], v[136:137], v[138:139]
	v_pk_fma_f32 v[14:15], v[14:15], v[136:137], v[138:139]
	v_pk_fma_f32 v[8:9], v[8:9], v[136:137], v[138:139]
	v_pk_fma_f32 v[10:11], v[10:11], v[136:137], v[138:139]
	v_pk_fma_f32 v[4:5], v[4:5], v[136:137], v[138:139]
	v_pk_fma_f32 v[6:7], v[6:7], v[136:137], v[138:139]
	v_cvt_pk_u8_f32 v148, v16, 0, 0
	v_cvt_pk_u8_f32 v149, v12, 0, 0
	v_cvt_pk_u8_f32 v150, v8, 0, 0
	v_cvt_pk_u8_f32 v151, v4, 0, 0
	v_cvt_pk_u8_f32 v148, v17, 1, v148
	v_cvt_pk_u8_f32 v149, v13, 1, v149
	v_cvt_pk_u8_f32 v150, v9, 1, v150
	v_cvt_pk_u8_f32 v151, v5, 1, v151
	v_cvt_pk_u8_f32 v148, v18, 2, v148
	v_cvt_pk_u8_f32 v149, v14, 2, v149
	v_cvt_pk_u8_f32 v150, v10, 2, v150
	v_cvt_pk_u8_f32 v151, v6, 2, v151
	v_cvt_pk_u8_f32 v148, v19, 3, v148
	v_cvt_pk_u8_f32 v149, v15, 3, v149
	v_cvt_pk_u8_f32 v150, v11, 3, v150
	v_cvt_pk_u8_f32 v151, v7, 3, v151
	v_mad_u64_u32 v[152:153], s[4:5], v194, s20, v[2:3]
	global_store_dwordx4 v152, v[148:151], s[72:73] nt
	s_andn2_b64 vcc, exec, s[74:75]
	s_mov_b64 s[4:5], -1
	s_cbranch_vccnz .LBB0_1263
	s_branch .LBB0_1539
